# final rmsnorm fast path (all loads up front, gains loaded once) on top of previous
# baseline (speedup 1.0000x reference)
; __device__ __forceinline__ void phase_final_norm(const bf16_t* Hb, const unsigned long long* ssq, const float* g, float* out, int gw, int ngw, int lane, float scale) {
;     for (int m = gw; m < MTOK; m += ngw) { const float rstd = scale / sqrtf((float)ssq[m] * (1.0f / 16777216.0f) * (1.0f / DM) + EPS);
;         const u32x4* xr = (const u32x4*)(Hb + (size_t)m * DM) + lane; f32x4* o = (f32x4*)(out + (size_t)m * DM); const f32x4* gr = (const f32x4*)g;
; __global__ void __launch_bounds__(NTHR, 2) hybrid_fwd(Args args) {
;     ...
;     if (IN(15)) phase_final_norm((const bf16_t*)(p.ws + WS_U), (const unsigned long long*)((const unsigned*)(p.ws + WS_CTL) + CW_SSQ) + 3 * MTOK, p.final_norm, p.out, gw, ngw, lane, FINAL_SCALE);
.LBB0_1877:
	s_cmp_lt_i32 s68, 16
	s_cselect_b64 s[0:1], -1, 0
	s_cmp_gt_i32 s69, 15
	s_cselect_b64 s[2:3], -1, 0
	s_and_b64 s[0:1], s[0:1], s[2:3]
	s_andn2_b64 vcc, exec, s[0:1]
	s_cbranch_vccnz .LBB0_1881
	s_cmpk_gt_i32 s52, 0x1fff
	s_cbranch_scc1 .LBB0_1881
	s_cmpk_eq_i32 s74, 0x800
	s_cbranch_scc1 .Lfn_entry
	s_ashr_i32 s53, s52, 31
	s_lshl_b64 s[0:1], s[52:53], 3
	s_add_u32 s11, s0, 0xb0000
	s_addc_u32 s12, s1, 0
	s_ashr_i32 s75, s74, 31
	s_lshl_b64 s[0:1], s[52:53], 13
	s_lshl_b64 s[2:3], s[74:75], 3
	s_waitcnt vmcnt(4)
	v_lshl_or_b32 v16, v164, 4, s0
	v_mov_b32_e32 v17, s1
	s_lshl_b64 s[4:5], s[74:75], 13
	s_lshl_b64 s[0:1], s[52:53], 14
	v_lshlrev_b32_e32 v0, 5, v164
	v_mov_b32_e32 v1, 0
	s_add_u32 s0, s56, s0
	v_or_b32_e32 v4, 0x1000, v0
	v_mov_b32_e32 v5, v1
	v_or_b32_e32 v6, 0x1800, v0
	v_mov_b32_e32 v7, v1
	v_or_b32_e32 v8, 0x2000, v0
	v_mov_b32_e32 v9, v1
	v_or_b32_e32 v10, 0x2800, v0
	v_mov_b32_e32 v11, v1
	v_or_b32_e32 v12, 0x3000, v0
	v_mov_b32_e32 v13, v1
	v_or_b32_e32 v14, 0x3800, v0
	v_mov_b32_e32 v15, v1
	s_addc_u32 s1, s57, s1
	s_waitcnt lgkmcnt(0)
	v_lshl_add_u64 v[2:3], s[54:55], 0, v[0:1]
	s_movk_i32 s8, 0x1000
	v_lshl_add_u64 v[4:5], s[54:55], 0, v[4:5]
	v_lshl_add_u64 v[6:7], s[54:55], 0, v[6:7]
	s_movk_i32 s9, 0x2000
	v_lshl_add_u64 v[8:9], s[54:55], 0, v[8:9]
	v_lshl_add_u64 v[10:11], s[54:55], 0, v[10:11]
	s_movk_i32 s10, 0x3000
	v_lshl_add_u64 v[12:13], s[54:55], 0, v[12:13]
	v_lshl_add_u64 v[14:15], s[54:55], 0, v[14:15]
	s_waitcnt vmcnt(3)
	v_lshl_add_u64 v[18:19], s[0:1], 0, v[0:1]
	s_lshl_b64 s[6:7], s[74:75], 14
	s_waitcnt vmcnt(2)
	v_mov_b32_e32 v24, 0x358637bd
	s_mov_b32 s13, 0xf800000
	v_mov_b32_e32 v25, 0x260
	s_mov_b32 s14, 0x2f800000
	s_mov_b32 s15, 0x2f801000

; __device__ __forceinline__ float bflo(unsigned w) { return __uint_as_float(w << 16); }
; __device__ __forceinline__ float bfhi(unsigned w) { return __uint_as_float(w & 0xffff0000u); }
; __device__ __forceinline__ void phase_final_norm(const bf16_t* Hb, const unsigned long long* ssq, const float* g, float* out, int gw, int ngw, int lane, float scale) {
;     for (int m = gw; m < MTOK; m += ngw) { const float rstd = scale / sqrtf((float)ssq[m] * (1.0f / 16777216.0f) * (1.0f / DM) + EPS);
;         const u32x4* xr = (const u32x4*)(Hb + (size_t)m * DM) + lane; f32x4* o = (f32x4*)(out + (size_t)m * DM); const f32x4* gr = (const f32x4*)g;
; #pragma unroll
;         for (int j = 0; j < 8; ++j) { const u32x4 r = xr[64 * j]; const int c4 = 2 * (64 * j + lane);
;             const f32x4 g0 = gr[c4], g1 = gr[c4 + 1];
;             o[c4] = (f32x4){bflo(r.x) * rstd * g0.x, bfhi(r.x) * rstd * g0.y, bflo(r.y) * rstd * g0.z, bfhi(r.y) * rstd * g0.w};
;             o[c4 + 1] = (f32x4){bflo(r.z) * rstd * g1.x, bfhi(r.z) * rstd * g1.y, bflo(r.w) * rstd * g1.z, bfhi(r.w) * rstd * g1.w}; } }
.Lfn_entry:
	v_lshlrev_b32_e32 v2, 4, v164
	v_lshlrev_b32_e32 v3, 5, v164
	v_mov_b32_e32 v232, 0
	s_add_u32 s20, s54, 0x1000
	s_addc_u32 s21, s55, 0
	s_add_u32 s22, s54, 0x2000
	s_addc_u32 s23, s55, 0
	s_add_u32 s24, s54, 0x3000
	s_addc_u32 s25, s55, 0
	global_load_dwordx4 v[8:11], v3, s[54:55] offset:0
	global_load_dwordx4 v[12:15], v3, s[54:55] offset:16
	global_load_dwordx4 v[16:19], v3, s[54:55] offset:2048
	global_load_dwordx4 v[20:23], v3, s[54:55] offset:2064
	global_load_dwordx4 v[24:27], v3, s[20:21] offset:0
	global_load_dwordx4 v[28:31], v3, s[20:21] offset:16
	global_load_dwordx4 v[32:35], v3, s[20:21] offset:2048
	global_load_dwordx4 v[36:39], v3, s[20:21] offset:2064
	global_load_dwordx4 v[40:43], v3, s[22:23] offset:0
	global_load_dwordx4 v[44:47], v3, s[22:23] offset:16
	global_load_dwordx4 v[48:51], v3, s[22:23] offset:2048
	global_load_dwordx4 v[52:55], v3, s[22:23] offset:2064
	global_load_dwordx4 v[56:59], v3, s[24:25] offset:0
	global_load_dwordx4 v[60:63], v3, s[24:25] offset:16
	global_load_dwordx4 v[64:67], v3, s[24:25] offset:2048
	global_load_dwordx4 v[68:71], v3, s[24:25] offset:2064
	s_add_u32 s4, s58, 0xb0000
	s_addc_u32 s5, s59, 0
	s_add_u32 s6, s58, 0x2f800000
	s_addc_u32 s7, s59, 0
	s_mov_b32 s26, s52
	s_lshl_b32 s27, s26, 3
	s_add_u32 s8, s4, s27
	s_addc_u32 s9, s5, 0
	global_load_dwordx2 v[200:201], v232, s[8:9]
	s_lshl_b32 s27, s26, 13
	s_add_u32 s8, s6, s27
	s_addc_u32 s9, s7, 0
	s_add_u32 s10, s8, 0x1000
	s_addc_u32 s11, s9, 0
	global_load_dwordx4 v[72:75], v2, s[8:9] offset:0
	global_load_dwordx4 v[76:79], v2, s[8:9] offset:1024
	global_load_dwordx4 v[80:83], v2, s[8:9] offset:2048
	global_load_dwordx4 v[84:87], v2, s[8:9] offset:3072
	global_load_dwordx4 v[88:91], v2, s[10:11] offset:0
	global_load_dwordx4 v[92:95], v2, s[10:11] offset:1024
	global_load_dwordx4 v[96:99], v2, s[10:11] offset:2048
	global_load_dwordx4 v[100:103], v2, s[10:11] offset:3072
	s_add_i32 s26, s26, s74
	s_lshl_b32 s27, s26, 3
	s_add_u32 s8, s4, s27
	s_addc_u32 s9, s5, 0
	global_load_dwordx2 v[202:203], v232, s[8:9]
	s_lshl_b32 s27, s26, 13
	s_add_u32 s8, s6, s27
	s_addc_u32 s9, s7, 0
	s_add_u32 s10, s8, 0x1000
	s_addc_u32 s11, s9, 0
	global_load_dwordx4 v[104:107], v2, s[8:9] offset:0
	global_load_dwordx4 v[108:111], v2, s[8:9] offset:1024
	global_load_dwordx4 v[112:115], v2, s[8:9] offset:2048
	global_load_dwordx4 v[116:119], v2, s[8:9] offset:3072
	global_load_dwordx4 v[120:123], v2, s[10:11] offset:0
	global_load_dwordx4 v[124:127], v2, s[10:11] offset:1024
	global_load_dwordx4 v[128:131], v2, s[10:11] offset:2048
	global_load_dwordx4 v[132:135], v2, s[10:11] offset:3072
	s_add_i32 s26, s26, s74
	s_lshl_b32 s27, s26, 3
	s_add_u32 s8, s4, s27
	s_addc_u32 s9, s5, 0
	global_load_dwordx2 v[204:205], v232, s[8:9]
	s_lshl_b32 s27, s26, 13
	s_add_u32 s8, s6, s27
	s_addc_u32 s9, s7, 0
	s_add_u32 s10, s8, 0x1000
	s_addc_u32 s11, s9, 0
	global_load_dwordx4 v[136:139], v2, s[8:9] offset:0
	global_load_dwordx4 v[140:143], v2, s[8:9] offset:1024
	global_load_dwordx4 v[144:147], v2, s[8:9] offset:2048
	global_load_dwordx4 v[148:151], v2, s[8:9] offset:3072
	global_load_dwordx4 v[152:155], v2, s[10:11] offset:0
	global_load_dwordx4 v[156:159], v2, s[10:11] offset:1024
	global_load_dwordx4 v[160:163], v2, s[10:11] offset:2048
	global_load_dwordx4 v[164:167], v2, s[10:11] offset:3072
	s_add_i32 s26, s26, s74
	s_lshl_b32 s27, s26, 3
	s_add_u32 s8, s4, s27
	s_addc_u32 s9, s5, 0
	global_load_dwordx2 v[206:207], v232, s[8:9]
	s_lshl_b32 s27, s26, 13
	s_add_u32 s8, s6, s27
	s_addc_u32 s9, s7, 0
	s_add_u32 s10, s8, 0x1000
	s_addc_u32 s11, s9, 0
	global_load_dwordx4 v[168:171], v2, s[8:9] offset:0
	global_load_dwordx4 v[172:175], v2, s[8:9] offset:1024
	global_load_dwordx4 v[176:179], v2, s[8:9] offset:2048
	global_load_dwordx4 v[180:183], v2, s[8:9] offset:3072
	global_load_dwordx4 v[184:187], v2, s[10:11] offset:0
	global_load_dwordx4 v[188:191], v2, s[10:11] offset:1024
	global_load_dwordx4 v[192:195], v2, s[10:11] offset:2048
	global_load_dwordx4 v[196:199], v2, s[10:11] offset:3072
	v_mov_b32_e32 v233, 0x358637bd
	v_mov_b32_e32 v234, 0x260
	s_mov_b32 s28, 0xf800000
	s_mov_b32 s26, s52
	s_lshl_b32 s27, s26, 14
	s_add_u32 s12, s56, s27
	s_addc_u32 s13, s57, 0
	s_add_u32 s14, s12, 0x1000
	s_addc_u32 s15, s13, 0
	s_add_u32 s16, s14, 0x1000
	s_addc_u32 s17, s15, 0
	s_add_u32 s18, s16, 0x1000
	s_addc_u32 s19, s17, 0
	s_waitcnt vmcnt(27)
; __device__ __forceinline__ float bflo(unsigned w) { return __uint_as_float(w << 16); }
; __device__ __forceinline__ float bfhi(unsigned w) { return __uint_as_float(w & 0xffff0000u); }
; __device__ __forceinline__ void phase_final_norm(const bf16_t* Hb, const unsigned long long* ssq, const float* g, float* out, int gw, int ngw, int lane, float scale) {
;     for (int m = gw; m < MTOK; m += ngw) { const float rstd = scale / sqrtf((float)ssq[m] * (1.0f / 16777216.0f) * (1.0f / DM) + EPS);
;         const u32x4* xr = (const u32x4*)(Hb + (size_t)m * DM) + lane; f32x4* o = (f32x4*)(out + (size_t)m * DM); const f32x4* gr = (const f32x4*)g;
; #pragma unroll
;         for (int j = 0; j < 8; ++j) { const u32x4 r = xr[64 * j]; const int c4 = 2 * (64 * j + lane);
;             const f32x4 g0 = gr[c4], g1 = gr[c4 + 1];
;             o[c4] = (f32x4){bflo(r.x) * rstd * g0.x, bfhi(r.x) * rstd * g0.y, bflo(r.y) * rstd * g0.z, bfhi(r.y) * rstd * g0.w};
;             o[c4 + 1] = (f32x4){bflo(r.z) * rstd * g1.x, bfhi(r.z) * rstd * g1.y, bflo(r.w) * rstd * g1.z, bfhi(r.w) * rstd * g1.w}; } }
	v_ffbh_u32_e32 v208, v201
	v_min_u32_e32 v208, 32, v208
	v_lshlrev_b64 v[200:201], v208, v[200:201]
	v_min_u32_e32 v200, 1, v200
	v_or_b32_e32 v200, v201, v200
	v_cvt_f32_u32_e32 v200, v200
	v_sub_u32_e32 v208, 32, v208
	v_ldexp_f32 v208, v200, v208
	v_mul_f32_e32 v208, 0x33800000, v208
	v_fmamk_f32 v208, v208, 0x39800000, v233
	v_mul_f32_e32 v209, 0x4f800000, v208
	v_cmp_gt_f32_e32 vcc, s28, v208
	s_nop 1
	v_cndmask_b32_e32 v208, v208, v209, vcc
	v_sqrt_f32_e32 v209, v208
	s_nop 1
	v_add_u32_e32 v210, -1, v209
	v_add_u32_e32 v211, 1, v209
	v_fma_f32 v212, -v210, v209, v208
	v_fma_f32 v213, -v211, v209, v208
	v_cmp_ge_f32_e64 s[0:1], 0, v212
	s_nop 1
	v_cndmask_b32_e64 v209, v209, v210, s[0:1]
	v_cmp_lt_f32_e64 s[0:1], 0, v213
	s_nop 1
	v_cndmask_b32_e64 v209, v209, v211, s[0:1]
	v_mul_f32_e32 v210, 0x37800000, v209
	v_cndmask_b32_e32 v209, v209, v210, vcc
	v_cmp_class_f32_e32 vcc, v208, v234
	s_nop 1
	v_cndmask_b32_e32 v208, v209, v208, vcc
	v_div_scale_f32 v209, s[0:1], v208, v208, 1.0
	v_rcp_f32_e32 v211, v209
	v_div_scale_f32 v210, vcc, 1.0, v208, 1.0
	s_nop 0
	v_fma_f32 v212, -v209, v211, 1.0
	v_fmac_f32_e32 v211, v212, v211
	v_mul_f32_e32 v212, v210, v211
	v_fma_f32 v213, -v209, v212, v210
	v_fmac_f32_e32 v212, v213, v211
	v_fma_f32 v209, -v209, v212, v210
	s_nop 1
	v_div_fmas_f32 v209, v209, v211, v212
	v_div_fixup_f32 v214, v209, v208, 1.0
	v_mov_b32_e32 v215, v214
	v_lshlrev_b32_e32 v216, 16, v72
	v_and_b32_e32 v217, 0xffff0000, v72
	v_lshlrev_b32_e32 v218, 16, v73
	v_and_b32_e32 v219, 0xffff0000, v73
	v_lshlrev_b32_e32 v220, 16, v74
	v_and_b32_e32 v221, 0xffff0000, v74
	v_lshlrev_b32_e32 v222, 16, v75
	v_and_b32_e32 v223, 0xffff0000, v75
	v_pk_mul_f32 v[216:217], v[214:215], v[216:217]
	v_pk_mul_f32 v[218:219], v[214:215], v[218:219]
	v_pk_mul_f32 v[220:221], v[214:215], v[220:221]
	v_pk_mul_f32 v[222:223], v[214:215], v[222:223]
	v_pk_mul_f32 v[216:217], v[8:9], v[216:217]
	v_pk_mul_f32 v[218:219], v[10:11], v[218:219]
	v_pk_mul_f32 v[220:221], v[12:13], v[220:221]
	v_pk_mul_f32 v[222:223], v[14:15], v[222:223]
	global_store_dwordx4 v3, v[216:219], s[12:13] offset:0
	global_store_dwordx4 v3, v[220:223], s[12:13] offset:16
	v_lshlrev_b32_e32 v224, 16, v76
	v_and_b32_e32 v225, 0xffff0000, v76
	v_lshlrev_b32_e32 v226, 16, v77
	v_and_b32_e32 v227, 0xffff0000, v77
	v_lshlrev_b32_e32 v228, 16, v78
	v_and_b32_e32 v229, 0xffff0000, v78
	v_lshlrev_b32_e32 v230, 16, v79
	v_and_b32_e32 v231, 0xffff0000, v79
	v_pk_mul_f32 v[224:225], v[214:215], v[224:225]
	v_pk_mul_f32 v[226:227], v[214:215], v[226:227]
	v_pk_mul_f32 v[228:229], v[214:215], v[228:229]
	v_pk_mul_f32 v[230:231], v[214:215], v[230:231]
	v_pk_mul_f32 v[224:225], v[16:17], v[224:225]
	v_pk_mul_f32 v[226:227], v[18:19], v[226:227]
	v_pk_mul_f32 v[228:229], v[20:21], v[228:229]
	v_pk_mul_f32 v[230:231], v[22:23], v[230:231]
	global_store_dwordx4 v3, v[224:227], s[12:13] offset:2048
	global_store_dwordx4 v3, v[228:231], s[12:13] offset:2064
	v_lshlrev_b32_e32 v216, 16, v80
	v_and_b32_e32 v217, 0xffff0000, v80
	v_lshlrev_b32_e32 v218, 16, v81
	v_and_b32_e32 v219, 0xffff0000, v81
	v_lshlrev_b32_e32 v220, 16, v82
	v_and_b32_e32 v221, 0xffff0000, v82
	v_lshlrev_b32_e32 v222, 16, v83
	v_and_b32_e32 v223, 0xffff0000, v83
	v_pk_mul_f32 v[216:217], v[214:215], v[216:217]
	v_pk_mul_f32 v[218:219], v[214:215], v[218:219]
	v_pk_mul_f32 v[220:221], v[214:215], v[220:221]
	v_pk_mul_f32 v[222:223], v[214:215], v[222:223]
	v_pk_mul_f32 v[216:217], v[24:25], v[216:217]
	v_pk_mul_f32 v[218:219], v[26:27], v[218:219]
	v_pk_mul_f32 v[220:221], v[28:29], v[220:221]
	v_pk_mul_f32 v[222:223], v[30:31], v[222:223]
	global_store_dwordx4 v3, v[216:219], s[14:15] offset:0
	global_store_dwordx4 v3, v[220:223], s[14:15] offset:16
	v_lshlrev_b32_e32 v224, 16, v84
	v_and_b32_e32 v225, 0xffff0000, v84
	v_lshlrev_b32_e32 v226, 16, v85
	v_and_b32_e32 v227, 0xffff0000, v85
	v_lshlrev_b32_e32 v228, 16, v86
	v_and_b32_e32 v229, 0xffff0000, v86
	v_lshlrev_b32_e32 v230, 16, v87
	v_and_b32_e32 v231, 0xffff0000, v87
	v_pk_mul_f32 v[224:225], v[214:215], v[224:225]
	v_pk_mul_f32 v[226:227], v[214:215], v[226:227]
	v_pk_mul_f32 v[228:229], v[214:215], v[228:229]
	v_pk_mul_f32 v[230:231], v[214:215], v[230:231]
	v_pk_mul_f32 v[224:225], v[32:33], v[224:225]
	v_pk_mul_f32 v[226:227], v[34:35], v[226:227]
	v_pk_mul_f32 v[228:229], v[36:37], v[228:229]
	v_pk_mul_f32 v[230:231], v[38:39], v[230:231]
	global_store_dwordx4 v3, v[224:227], s[14:15] offset:2048
	global_store_dwordx4 v3, v[228:231], s[14:15] offset:2064
	v_lshlrev_b32_e32 v216, 16, v88
	v_and_b32_e32 v217, 0xffff0000, v88
	v_lshlrev_b32_e32 v218, 16, v89
	v_and_b32_e32 v219, 0xffff0000, v89
	v_lshlrev_b32_e32 v220, 16, v90
	v_and_b32_e32 v221, 0xffff0000, v90
	v_lshlrev_b32_e32 v222, 16, v91
	v_and_b32_e32 v223, 0xffff0000, v91
	v_pk_mul_f32 v[216:217], v[214:215], v[216:217]
	v_pk_mul_f32 v[218:219], v[214:215], v[218:219]
	v_pk_mul_f32 v[220:221], v[214:215], v[220:221]
	v_pk_mul_f32 v[222:223], v[214:215], v[222:223]
	v_pk_mul_f32 v[216:217], v[40:41], v[216:217]
	v_pk_mul_f32 v[218:219], v[42:43], v[218:219]
	v_pk_mul_f32 v[220:221], v[44:45], v[220:221]
	v_pk_mul_f32 v[222:223], v[46:47], v[222:223]
	global_store_dwordx4 v3, v[216:219], s[16:17] offset:0
	global_store_dwordx4 v3, v[220:223], s[16:17] offset:16
	v_lshlrev_b32_e32 v224, 16, v92
	v_and_b32_e32 v225, 0xffff0000, v92
	v_lshlrev_b32_e32 v226, 16, v93
	v_and_b32_e32 v227, 0xffff0000, v93
	v_lshlrev_b32_e32 v228, 16, v94
	v_and_b32_e32 v229, 0xffff0000, v94
	v_lshlrev_b32_e32 v230, 16, v95
	v_and_b32_e32 v231, 0xffff0000, v95
	v_pk_mul_f32 v[224:225], v[214:215], v[224:225]
; __device__ __forceinline__ float bflo(unsigned w) { return __uint_as_float(w << 16); }
; __device__ __forceinline__ float bfhi(unsigned w) { return __uint_as_float(w & 0xffff0000u); }
; __device__ __forceinline__ void phase_final_norm(const bf16_t* Hb, const unsigned long long* ssq, const float* g, float* out, int gw, int ngw, int lane, float scale) {
;     for (int m = gw; m < MTOK; m += ngw) { const float rstd = scale / sqrtf((float)ssq[m] * (1.0f / 16777216.0f) * (1.0f / DM) + EPS);
;         const u32x4* xr = (const u32x4*)(Hb + (size_t)m * DM) + lane; f32x4* o = (f32x4*)(out + (size_t)m * DM); const f32x4* gr = (const f32x4*)g;
; #pragma unroll
;         for (int j = 0; j < 8; ++j) { const u32x4 r = xr[64 * j]; const int c4 = 2 * (64 * j + lane);
;             const f32x4 g0 = gr[c4], g1 = gr[c4 + 1];
;             o[c4] = (f32x4){bflo(r.x) * rstd * g0.x, bfhi(r.x) * rstd * g0.y, bflo(r.y) * rstd * g0.z, bfhi(r.y) * rstd * g0.w};
;             o[c4 + 1] = (f32x4){bflo(r.z) * rstd * g1.x, bfhi(r.z) * rstd * g1.y, bflo(r.w) * rstd * g1.z, bfhi(r.w) * rstd * g1.w}; } }
	v_pk_mul_f32 v[226:227], v[214:215], v[226:227]
	v_pk_mul_f32 v[228:229], v[214:215], v[228:229]
	v_pk_mul_f32 v[230:231], v[214:215], v[230:231]
	v_pk_mul_f32 v[224:225], v[48:49], v[224:225]
	v_pk_mul_f32 v[226:227], v[50:51], v[226:227]
	v_pk_mul_f32 v[228:229], v[52:53], v[228:229]
	v_pk_mul_f32 v[230:231], v[54:55], v[230:231]
	global_store_dwordx4 v3, v[224:227], s[16:17] offset:2048
	global_store_dwordx4 v3, v[228:231], s[16:17] offset:2064
	v_lshlrev_b32_e32 v216, 16, v96
	v_and_b32_e32 v217, 0xffff0000, v96
	v_lshlrev_b32_e32 v218, 16, v97
	v_and_b32_e32 v219, 0xffff0000, v97
	v_lshlrev_b32_e32 v220, 16, v98
	v_and_b32_e32 v221, 0xffff0000, v98
	v_lshlrev_b32_e32 v222, 16, v99
	v_and_b32_e32 v223, 0xffff0000, v99
	v_pk_mul_f32 v[216:217], v[214:215], v[216:217]
	v_pk_mul_f32 v[218:219], v[214:215], v[218:219]
	v_pk_mul_f32 v[220:221], v[214:215], v[220:221]
	v_pk_mul_f32 v[222:223], v[214:215], v[222:223]
	v_pk_mul_f32 v[216:217], v[56:57], v[216:217]
	v_pk_mul_f32 v[218:219], v[58:59], v[218:219]
	v_pk_mul_f32 v[220:221], v[60:61], v[220:221]
	v_pk_mul_f32 v[222:223], v[62:63], v[222:223]
	global_store_dwordx4 v3, v[216:219], s[18:19] offset:0
	global_store_dwordx4 v3, v[220:223], s[18:19] offset:16
	v_lshlrev_b32_e32 v224, 16, v100
	v_and_b32_e32 v225, 0xffff0000, v100
	v_lshlrev_b32_e32 v226, 16, v101
	v_and_b32_e32 v227, 0xffff0000, v101
	v_lshlrev_b32_e32 v228, 16, v102
	v_and_b32_e32 v229, 0xffff0000, v102
	v_lshlrev_b32_e32 v230, 16, v103
	v_and_b32_e32 v231, 0xffff0000, v103
	v_pk_mul_f32 v[224:225], v[214:215], v[224:225]
	v_pk_mul_f32 v[226:227], v[214:215], v[226:227]
	v_pk_mul_f32 v[228:229], v[214:215], v[228:229]
	v_pk_mul_f32 v[230:231], v[214:215], v[230:231]
	v_pk_mul_f32 v[224:225], v[64:65], v[224:225]
	v_pk_mul_f32 v[226:227], v[66:67], v[226:227]
	v_pk_mul_f32 v[228:229], v[68:69], v[228:229]
	v_pk_mul_f32 v[230:231], v[70:71], v[230:231]
	global_store_dwordx4 v3, v[224:227], s[18:19] offset:2048
	global_store_dwordx4 v3, v[228:231], s[18:19] offset:2064
	s_add_i32 s26, s26, s74
	s_lshl_b32 s27, s26, 14
	s_add_u32 s12, s56, s27
	s_addc_u32 s13, s57, 0
	s_add_u32 s14, s12, 0x1000
	s_addc_u32 s15, s13, 0
	s_add_u32 s16, s14, 0x1000
	s_addc_u32 s17, s15, 0
	s_add_u32 s18, s16, 0x1000
	s_addc_u32 s19, s17, 0
	s_waitcnt vmcnt(34)
	v_ffbh_u32_e32 v208, v203
	v_min_u32_e32 v208, 32, v208
	v_lshlrev_b64 v[202:203], v208, v[202:203]
	v_min_u32_e32 v202, 1, v202
	v_or_b32_e32 v202, v203, v202
	v_cvt_f32_u32_e32 v202, v202
	v_sub_u32_e32 v208, 32, v208
	v_ldexp_f32 v208, v202, v208
	v_mul_f32_e32 v208, 0x33800000, v208
	v_fmamk_f32 v208, v208, 0x39800000, v233
	v_mul_f32_e32 v209, 0x4f800000, v208
	v_cmp_gt_f32_e32 vcc, s28, v208
	s_nop 1
	v_cndmask_b32_e32 v208, v208, v209, vcc
	v_sqrt_f32_e32 v209, v208
	s_nop 1
	v_add_u32_e32 v210, -1, v209
	v_add_u32_e32 v211, 1, v209
	v_fma_f32 v212, -v210, v209, v208
	v_fma_f32 v213, -v211, v209, v208
	v_cmp_ge_f32_e64 s[0:1], 0, v212
	s_nop 1
	v_cndmask_b32_e64 v209, v209, v210, s[0:1]
	v_cmp_lt_f32_e64 s[0:1], 0, v213
	s_nop 1
	v_cndmask_b32_e64 v209, v209, v211, s[0:1]
	v_mul_f32_e32 v210, 0x37800000, v209
	v_cndmask_b32_e32 v209, v209, v210, vcc
	v_cmp_class_f32_e32 vcc, v208, v234
	s_nop 1
	v_cndmask_b32_e32 v208, v209, v208, vcc
	v_div_scale_f32 v209, s[0:1], v208, v208, 1.0
	v_rcp_f32_e32 v211, v209
	v_div_scale_f32 v210, vcc, 1.0, v208, 1.0
	s_nop 0
	v_fma_f32 v212, -v209, v211, 1.0
	v_fmac_f32_e32 v211, v212, v211
	v_mul_f32_e32 v212, v210, v211
	v_fma_f32 v213, -v209, v212, v210
	v_fmac_f32_e32 v212, v213, v211
	v_fma_f32 v209, -v209, v212, v210
	s_nop 1
	v_div_fmas_f32 v209, v209, v211, v212
	v_div_fixup_f32 v214, v209, v208, 1.0
	v_mov_b32_e32 v215, v214
	v_lshlrev_b32_e32 v216, 16, v104
	v_and_b32_e32 v217, 0xffff0000, v104
	v_lshlrev_b32_e32 v218, 16, v105
	v_and_b32_e32 v219, 0xffff0000, v105
	v_lshlrev_b32_e32 v220, 16, v106
	v_and_b32_e32 v221, 0xffff0000, v106
	v_lshlrev_b32_e32 v222, 16, v107
	v_and_b32_e32 v223, 0xffff0000, v107
	v_pk_mul_f32 v[216:217], v[214:215], v[216:217]
	v_pk_mul_f32 v[218:219], v[214:215], v[218:219]
	v_pk_mul_f32 v[220:221], v[214:215], v[220:221]
	v_pk_mul_f32 v[222:223], v[214:215], v[222:223]
	v_pk_mul_f32 v[216:217], v[8:9], v[216:217]
	v_pk_mul_f32 v[218:219], v[10:11], v[218:219]
	v_pk_mul_f32 v[220:221], v[12:13], v[220:221]
	v_pk_mul_f32 v[222:223], v[14:15], v[222:223]
	global_store_dwordx4 v3, v[216:219], s[12:13] offset:0
	global_store_dwordx4 v3, v[220:223], s[12:13] offset:16
	v_lshlrev_b32_e32 v224, 16, v108
	v_and_b32_e32 v225, 0xffff0000, v108
	v_lshlrev_b32_e32 v226, 16, v109
	v_and_b32_e32 v227, 0xffff0000, v109
	v_lshlrev_b32_e32 v228, 16, v110
	v_and_b32_e32 v229, 0xffff0000, v110
	v_lshlrev_b32_e32 v230, 16, v111
	v_and_b32_e32 v231, 0xffff0000, v111
	v_pk_mul_f32 v[224:225], v[214:215], v[224:225]
	v_pk_mul_f32 v[226:227], v[214:215], v[226:227]
	v_pk_mul_f32 v[228:229], v[214:215], v[228:229]
	v_pk_mul_f32 v[230:231], v[214:215], v[230:231]
	v_pk_mul_f32 v[224:225], v[16:17], v[224:225]
	v_pk_mul_f32 v[226:227], v[18:19], v[226:227]
	v_pk_mul_f32 v[228:229], v[20:21], v[228:229]
	v_pk_mul_f32 v[230:231], v[22:23], v[230:231]
	global_store_dwordx4 v3, v[224:227], s[12:13] offset:2048
	global_store_dwordx4 v3, v[228:231], s[12:13] offset:2064
	v_lshlrev_b32_e32 v216, 16, v112
	v_and_b32_e32 v217, 0xffff0000, v112
	v_lshlrev_b32_e32 v218, 16, v113
	v_and_b32_e32 v219, 0xffff0000, v113
	v_lshlrev_b32_e32 v220, 16, v114
	v_and_b32_e32 v221, 0xffff0000, v114
	v_lshlrev_b32_e32 v222, 16, v115
	v_and_b32_e32 v223, 0xffff0000, v115
	v_pk_mul_f32 v[216:217], v[214:215], v[216:217]
	v_pk_mul_f32 v[218:219], v[214:215], v[218:219]
; __device__ __forceinline__ float bflo(unsigned w) { return __uint_as_float(w << 16); }
; __device__ __forceinline__ float bfhi(unsigned w) { return __uint_as_float(w & 0xffff0000u); }
; __device__ __forceinline__ void phase_final_norm(const bf16_t* Hb, const unsigned long long* ssq, const float* g, float* out, int gw, int ngw, int lane, float scale) {
;     for (int m = gw; m < MTOK; m += ngw) { const float rstd = scale / sqrtf((float)ssq[m] * (1.0f / 16777216.0f) * (1.0f / DM) + EPS);
;         const u32x4* xr = (const u32x4*)(Hb + (size_t)m * DM) + lane; f32x4* o = (f32x4*)(out + (size_t)m * DM); const f32x4* gr = (const f32x4*)g;
; #pragma unroll
;         for (int j = 0; j < 8; ++j) { const u32x4 r = xr[64 * j]; const int c4 = 2 * (64 * j + lane);
;             const f32x4 g0 = gr[c4], g1 = gr[c4 + 1];
;             o[c4] = (f32x4){bflo(r.x) * rstd * g0.x, bfhi(r.x) * rstd * g0.y, bflo(r.y) * rstd * g0.z, bfhi(r.y) * rstd * g0.w};
;             o[c4 + 1] = (f32x4){bflo(r.z) * rstd * g1.x, bfhi(r.z) * rstd * g1.y, bflo(r.w) * rstd * g1.z, bfhi(r.w) * rstd * g1.w}; } }
	v_pk_mul_f32 v[220:221], v[214:215], v[220:221]
	v_pk_mul_f32 v[222:223], v[214:215], v[222:223]
	v_pk_mul_f32 v[216:217], v[24:25], v[216:217]
	v_pk_mul_f32 v[218:219], v[26:27], v[218:219]
	v_pk_mul_f32 v[220:221], v[28:29], v[220:221]
	v_pk_mul_f32 v[222:223], v[30:31], v[222:223]
	global_store_dwordx4 v3, v[216:219], s[14:15] offset:0
	global_store_dwordx4 v3, v[220:223], s[14:15] offset:16
	v_lshlrev_b32_e32 v224, 16, v116
	v_and_b32_e32 v225, 0xffff0000, v116
	v_lshlrev_b32_e32 v226, 16, v117
	v_and_b32_e32 v227, 0xffff0000, v117
	v_lshlrev_b32_e32 v228, 16, v118
	v_and_b32_e32 v229, 0xffff0000, v118
	v_lshlrev_b32_e32 v230, 16, v119
	v_and_b32_e32 v231, 0xffff0000, v119
	v_pk_mul_f32 v[224:225], v[214:215], v[224:225]
	v_pk_mul_f32 v[226:227], v[214:215], v[226:227]
	v_pk_mul_f32 v[228:229], v[214:215], v[228:229]
	v_pk_mul_f32 v[230:231], v[214:215], v[230:231]
	v_pk_mul_f32 v[224:225], v[32:33], v[224:225]
	v_pk_mul_f32 v[226:227], v[34:35], v[226:227]
	v_pk_mul_f32 v[228:229], v[36:37], v[228:229]
	v_pk_mul_f32 v[230:231], v[38:39], v[230:231]
	global_store_dwordx4 v3, v[224:227], s[14:15] offset:2048
	global_store_dwordx4 v3, v[228:231], s[14:15] offset:2064
	v_lshlrev_b32_e32 v216, 16, v120
	v_and_b32_e32 v217, 0xffff0000, v120
	v_lshlrev_b32_e32 v218, 16, v121
	v_and_b32_e32 v219, 0xffff0000, v121
	v_lshlrev_b32_e32 v220, 16, v122
	v_and_b32_e32 v221, 0xffff0000, v122
	v_lshlrev_b32_e32 v222, 16, v123
	v_and_b32_e32 v223, 0xffff0000, v123
	v_pk_mul_f32 v[216:217], v[214:215], v[216:217]
	v_pk_mul_f32 v[218:219], v[214:215], v[218:219]
	v_pk_mul_f32 v[220:221], v[214:215], v[220:221]
	v_pk_mul_f32 v[222:223], v[214:215], v[222:223]
	v_pk_mul_f32 v[216:217], v[40:41], v[216:217]
	v_pk_mul_f32 v[218:219], v[42:43], v[218:219]
	v_pk_mul_f32 v[220:221], v[44:45], v[220:221]
	v_pk_mul_f32 v[222:223], v[46:47], v[222:223]
	global_store_dwordx4 v3, v[216:219], s[16:17] offset:0
	global_store_dwordx4 v3, v[220:223], s[16:17] offset:16
	v_lshlrev_b32_e32 v224, 16, v124
	v_and_b32_e32 v225, 0xffff0000, v124
	v_lshlrev_b32_e32 v226, 16, v125
	v_and_b32_e32 v227, 0xffff0000, v125
	v_lshlrev_b32_e32 v228, 16, v126
	v_and_b32_e32 v229, 0xffff0000, v126
	v_lshlrev_b32_e32 v230, 16, v127
	v_and_b32_e32 v231, 0xffff0000, v127
	v_pk_mul_f32 v[224:225], v[214:215], v[224:225]
	v_pk_mul_f32 v[226:227], v[214:215], v[226:227]
	v_pk_mul_f32 v[228:229], v[214:215], v[228:229]
	v_pk_mul_f32 v[230:231], v[214:215], v[230:231]
	v_pk_mul_f32 v[224:225], v[48:49], v[224:225]
	v_pk_mul_f32 v[226:227], v[50:51], v[226:227]
	v_pk_mul_f32 v[228:229], v[52:53], v[228:229]
	v_pk_mul_f32 v[230:231], v[54:55], v[230:231]
	global_store_dwordx4 v3, v[224:227], s[16:17] offset:2048
	global_store_dwordx4 v3, v[228:231], s[16:17] offset:2064
	v_lshlrev_b32_e32 v216, 16, v128
	v_and_b32_e32 v217, 0xffff0000, v128
	v_lshlrev_b32_e32 v218, 16, v129
	v_and_b32_e32 v219, 0xffff0000, v129
	v_lshlrev_b32_e32 v220, 16, v130
	v_and_b32_e32 v221, 0xffff0000, v130
	v_lshlrev_b32_e32 v222, 16, v131
	v_and_b32_e32 v223, 0xffff0000, v131
	v_pk_mul_f32 v[216:217], v[214:215], v[216:217]
	v_pk_mul_f32 v[218:219], v[214:215], v[218:219]
	v_pk_mul_f32 v[220:221], v[214:215], v[220:221]
	v_pk_mul_f32 v[222:223], v[214:215], v[222:223]
	v_pk_mul_f32 v[216:217], v[56:57], v[216:217]
	v_pk_mul_f32 v[218:219], v[58:59], v[218:219]
	v_pk_mul_f32 v[220:221], v[60:61], v[220:221]
	v_pk_mul_f32 v[222:223], v[62:63], v[222:223]
	global_store_dwordx4 v3, v[216:219], s[18:19] offset:0
	global_store_dwordx4 v3, v[220:223], s[18:19] offset:16
	v_lshlrev_b32_e32 v224, 16, v132
	v_and_b32_e32 v225, 0xffff0000, v132
	v_lshlrev_b32_e32 v226, 16, v133
	v_and_b32_e32 v227, 0xffff0000, v133
	v_lshlrev_b32_e32 v228, 16, v134
	v_and_b32_e32 v229, 0xffff0000, v134
	v_lshlrev_b32_e32 v230, 16, v135
	v_and_b32_e32 v231, 0xffff0000, v135
	v_pk_mul_f32 v[224:225], v[214:215], v[224:225]
	v_pk_mul_f32 v[226:227], v[214:215], v[226:227]
	v_pk_mul_f32 v[228:229], v[214:215], v[228:229]
	v_pk_mul_f32 v[230:231], v[214:215], v[230:231]
	v_pk_mul_f32 v[224:225], v[64:65], v[224:225]
	v_pk_mul_f32 v[226:227], v[66:67], v[226:227]
	v_pk_mul_f32 v[228:229], v[68:69], v[228:229]
	v_pk_mul_f32 v[230:231], v[70:71], v[230:231]
	global_store_dwordx4 v3, v[224:227], s[18:19] offset:2048
	global_store_dwordx4 v3, v[228:231], s[18:19] offset:2064
	s_add_i32 s26, s26, s74
	s_lshl_b32 s27, s26, 14
	s_add_u32 s12, s56, s27
	s_addc_u32 s13, s57, 0
	s_add_u32 s14, s12, 0x1000
	s_addc_u32 s15, s13, 0
	s_add_u32 s16, s14, 0x1000
	s_addc_u32 s17, s15, 0
	s_add_u32 s18, s16, 0x1000
	s_addc_u32 s19, s17, 0
	s_waitcnt vmcnt(41)
; __device__ __forceinline__ float bflo(unsigned w) { return __uint_as_float(w << 16); }
; __device__ __forceinline__ float bfhi(unsigned w) { return __uint_as_float(w & 0xffff0000u); }
; __device__ __forceinline__ void phase_final_norm(const bf16_t* Hb, const unsigned long long* ssq, const float* g, float* out, int gw, int ngw, int lane, float scale) {
;     for (int m = gw; m < MTOK; m += ngw) { const float rstd = scale / sqrtf((float)ssq[m] * (1.0f / 16777216.0f) * (1.0f / DM) + EPS);
;         const u32x4* xr = (const u32x4*)(Hb + (size_t)m * DM) + lane; f32x4* o = (f32x4*)(out + (size_t)m * DM); const f32x4* gr = (const f32x4*)g;
; #pragma unroll
;         for (int j = 0; j < 8; ++j) { const u32x4 r = xr[64 * j]; const int c4 = 2 * (64 * j + lane);
;             const f32x4 g0 = gr[c4], g1 = gr[c4 + 1];
;             o[c4] = (f32x4){bflo(r.x) * rstd * g0.x, bfhi(r.x) * rstd * g0.y, bflo(r.y) * rstd * g0.z, bfhi(r.y) * rstd * g0.w};
;             o[c4 + 1] = (f32x4){bflo(r.z) * rstd * g1.x, bfhi(r.z) * rstd * g1.y, bflo(r.w) * rstd * g1.z, bfhi(r.w) * rstd * g1.w}; } }
	v_ffbh_u32_e32 v208, v205
	v_min_u32_e32 v208, 32, v208
	v_lshlrev_b64 v[204:205], v208, v[204:205]
	v_min_u32_e32 v204, 1, v204
	v_or_b32_e32 v204, v205, v204
	v_cvt_f32_u32_e32 v204, v204
	v_sub_u32_e32 v208, 32, v208
	v_ldexp_f32 v208, v204, v208
	v_mul_f32_e32 v208, 0x33800000, v208
	v_fmamk_f32 v208, v208, 0x39800000, v233
	v_mul_f32_e32 v209, 0x4f800000, v208
	v_cmp_gt_f32_e32 vcc, s28, v208
	s_nop 1
	v_cndmask_b32_e32 v208, v208, v209, vcc
	v_sqrt_f32_e32 v209, v208
	s_nop 1
	v_add_u32_e32 v210, -1, v209
	v_add_u32_e32 v211, 1, v209
	v_fma_f32 v212, -v210, v209, v208
	v_fma_f32 v213, -v211, v209, v208
	v_cmp_ge_f32_e64 s[0:1], 0, v212
	s_nop 1
	v_cndmask_b32_e64 v209, v209, v210, s[0:1]
	v_cmp_lt_f32_e64 s[0:1], 0, v213
	s_nop 1
	v_cndmask_b32_e64 v209, v209, v211, s[0:1]
	v_mul_f32_e32 v210, 0x37800000, v209
	v_cndmask_b32_e32 v209, v209, v210, vcc
	v_cmp_class_f32_e32 vcc, v208, v234
	s_nop 1
	v_cndmask_b32_e32 v208, v209, v208, vcc
	v_div_scale_f32 v209, s[0:1], v208, v208, 1.0
	v_rcp_f32_e32 v211, v209
	v_div_scale_f32 v210, vcc, 1.0, v208, 1.0
	s_nop 0
	v_fma_f32 v212, -v209, v211, 1.0
	v_fmac_f32_e32 v211, v212, v211
	v_mul_f32_e32 v212, v210, v211
	v_fma_f32 v213, -v209, v212, v210
	v_fmac_f32_e32 v212, v213, v211
	v_fma_f32 v209, -v209, v212, v210
	s_nop 1
	v_div_fmas_f32 v209, v209, v211, v212
	v_div_fixup_f32 v214, v209, v208, 1.0
	v_mov_b32_e32 v215, v214
	v_lshlrev_b32_e32 v216, 16, v136
	v_and_b32_e32 v217, 0xffff0000, v136
	v_lshlrev_b32_e32 v218, 16, v137
	v_and_b32_e32 v219, 0xffff0000, v137
	v_lshlrev_b32_e32 v220, 16, v138
	v_and_b32_e32 v221, 0xffff0000, v138
	v_lshlrev_b32_e32 v222, 16, v139
	v_and_b32_e32 v223, 0xffff0000, v139
	v_pk_mul_f32 v[216:217], v[214:215], v[216:217]
	v_pk_mul_f32 v[218:219], v[214:215], v[218:219]
	v_pk_mul_f32 v[220:221], v[214:215], v[220:221]
	v_pk_mul_f32 v[222:223], v[214:215], v[222:223]
	v_pk_mul_f32 v[216:217], v[8:9], v[216:217]
	v_pk_mul_f32 v[218:219], v[10:11], v[218:219]
	v_pk_mul_f32 v[220:221], v[12:13], v[220:221]
	v_pk_mul_f32 v[222:223], v[14:15], v[222:223]
	global_store_dwordx4 v3, v[216:219], s[12:13] offset:0
	global_store_dwordx4 v3, v[220:223], s[12:13] offset:16
	v_lshlrev_b32_e32 v224, 16, v140
	v_and_b32_e32 v225, 0xffff0000, v140
	v_lshlrev_b32_e32 v226, 16, v141
	v_and_b32_e32 v227, 0xffff0000, v141
	v_lshlrev_b32_e32 v228, 16, v142
	v_and_b32_e32 v229, 0xffff0000, v142
	v_lshlrev_b32_e32 v230, 16, v143
	v_and_b32_e32 v231, 0xffff0000, v143
	v_pk_mul_f32 v[224:225], v[214:215], v[224:225]
	v_pk_mul_f32 v[226:227], v[214:215], v[226:227]
	v_pk_mul_f32 v[228:229], v[214:215], v[228:229]
	v_pk_mul_f32 v[230:231], v[214:215], v[230:231]
	v_pk_mul_f32 v[224:225], v[16:17], v[224:225]
	v_pk_mul_f32 v[226:227], v[18:19], v[226:227]
	v_pk_mul_f32 v[228:229], v[20:21], v[228:229]
	v_pk_mul_f32 v[230:231], v[22:23], v[230:231]
	global_store_dwordx4 v3, v[224:227], s[12:13] offset:2048
	global_store_dwordx4 v3, v[228:231], s[12:13] offset:2064
	v_lshlrev_b32_e32 v216, 16, v144
	v_and_b32_e32 v217, 0xffff0000, v144
	v_lshlrev_b32_e32 v218, 16, v145
	v_and_b32_e32 v219, 0xffff0000, v145
	v_lshlrev_b32_e32 v220, 16, v146
	v_and_b32_e32 v221, 0xffff0000, v146
	v_lshlrev_b32_e32 v222, 16, v147
	v_and_b32_e32 v223, 0xffff0000, v147
	v_pk_mul_f32 v[216:217], v[214:215], v[216:217]
	v_pk_mul_f32 v[218:219], v[214:215], v[218:219]
	v_pk_mul_f32 v[220:221], v[214:215], v[220:221]
	v_pk_mul_f32 v[222:223], v[214:215], v[222:223]
	v_pk_mul_f32 v[216:217], v[24:25], v[216:217]
	v_pk_mul_f32 v[218:219], v[26:27], v[218:219]
	v_pk_mul_f32 v[220:221], v[28:29], v[220:221]
	v_pk_mul_f32 v[222:223], v[30:31], v[222:223]
	global_store_dwordx4 v3, v[216:219], s[14:15] offset:0
	global_store_dwordx4 v3, v[220:223], s[14:15] offset:16
	v_lshlrev_b32_e32 v224, 16, v148
	v_and_b32_e32 v225, 0xffff0000, v148
	v_lshlrev_b32_e32 v226, 16, v149
	v_and_b32_e32 v227, 0xffff0000, v149
	v_lshlrev_b32_e32 v228, 16, v150
	v_and_b32_e32 v229, 0xffff0000, v150
	v_lshlrev_b32_e32 v230, 16, v151
	v_and_b32_e32 v231, 0xffff0000, v151
	v_pk_mul_f32 v[224:225], v[214:215], v[224:225]
	v_pk_mul_f32 v[226:227], v[214:215], v[226:227]
	v_pk_mul_f32 v[228:229], v[214:215], v[228:229]
	v_pk_mul_f32 v[230:231], v[214:215], v[230:231]
	v_pk_mul_f32 v[224:225], v[32:33], v[224:225]
	v_pk_mul_f32 v[226:227], v[34:35], v[226:227]
	v_pk_mul_f32 v[228:229], v[36:37], v[228:229]
	v_pk_mul_f32 v[230:231], v[38:39], v[230:231]
	global_store_dwordx4 v3, v[224:227], s[14:15] offset:2048
	global_store_dwordx4 v3, v[228:231], s[14:15] offset:2064
	v_lshlrev_b32_e32 v216, 16, v152
	v_and_b32_e32 v217, 0xffff0000, v152
	v_lshlrev_b32_e32 v218, 16, v153
	v_and_b32_e32 v219, 0xffff0000, v153
	v_lshlrev_b32_e32 v220, 16, v154
	v_and_b32_e32 v221, 0xffff0000, v154
	v_lshlrev_b32_e32 v222, 16, v155
	v_and_b32_e32 v223, 0xffff0000, v155
	v_pk_mul_f32 v[216:217], v[214:215], v[216:217]
	v_pk_mul_f32 v[218:219], v[214:215], v[218:219]
	v_pk_mul_f32 v[220:221], v[214:215], v[220:221]
	v_pk_mul_f32 v[222:223], v[214:215], v[222:223]
	v_pk_mul_f32 v[216:217], v[40:41], v[216:217]
	v_pk_mul_f32 v[218:219], v[42:43], v[218:219]
	v_pk_mul_f32 v[220:221], v[44:45], v[220:221]
	v_pk_mul_f32 v[222:223], v[46:47], v[222:223]
	global_store_dwordx4 v3, v[216:219], s[16:17] offset:0
	global_store_dwordx4 v3, v[220:223], s[16:17] offset:16
	v_lshlrev_b32_e32 v224, 16, v156
	v_and_b32_e32 v225, 0xffff0000, v156
	v_lshlrev_b32_e32 v226, 16, v157
	v_and_b32_e32 v227, 0xffff0000, v157
	v_lshlrev_b32_e32 v228, 16, v158
	v_and_b32_e32 v229, 0xffff0000, v158
	v_lshlrev_b32_e32 v230, 16, v159
	v_and_b32_e32 v231, 0xffff0000, v159
; __device__ __forceinline__ float bflo(unsigned w) { return __uint_as_float(w << 16); }
; __device__ __forceinline__ float bfhi(unsigned w) { return __uint_as_float(w & 0xffff0000u); }
; __device__ __forceinline__ void phase_final_norm(const bf16_t* Hb, const unsigned long long* ssq, const float* g, float* out, int gw, int ngw, int lane, float scale) {
;     for (int m = gw; m < MTOK; m += ngw) { const float rstd = scale / sqrtf((float)ssq[m] * (1.0f / 16777216.0f) * (1.0f / DM) + EPS);
;         const u32x4* xr = (const u32x4*)(Hb + (size_t)m * DM) + lane; f32x4* o = (f32x4*)(out + (size_t)m * DM); const f32x4* gr = (const f32x4*)g;
; #pragma unroll
;         for (int j = 0; j < 8; ++j) { const u32x4 r = xr[64 * j]; const int c4 = 2 * (64 * j + lane);
;             const f32x4 g0 = gr[c4], g1 = gr[c4 + 1];
;             o[c4] = (f32x4){bflo(r.x) * rstd * g0.x, bfhi(r.x) * rstd * g0.y, bflo(r.y) * rstd * g0.z, bfhi(r.y) * rstd * g0.w};
;             o[c4 + 1] = (f32x4){bflo(r.z) * rstd * g1.x, bfhi(r.z) * rstd * g1.y, bflo(r.w) * rstd * g1.z, bfhi(r.w) * rstd * g1.w}; } }
	v_pk_mul_f32 v[224:225], v[214:215], v[224:225]
	v_pk_mul_f32 v[226:227], v[214:215], v[226:227]
	v_pk_mul_f32 v[228:229], v[214:215], v[228:229]
	v_pk_mul_f32 v[230:231], v[214:215], v[230:231]
	v_pk_mul_f32 v[224:225], v[48:49], v[224:225]
	v_pk_mul_f32 v[226:227], v[50:51], v[226:227]
	v_pk_mul_f32 v[228:229], v[52:53], v[228:229]
	v_pk_mul_f32 v[230:231], v[54:55], v[230:231]
	global_store_dwordx4 v3, v[224:227], s[16:17] offset:2048
	global_store_dwordx4 v3, v[228:231], s[16:17] offset:2064
	v_lshlrev_b32_e32 v216, 16, v160
	v_and_b32_e32 v217, 0xffff0000, v160
	v_lshlrev_b32_e32 v218, 16, v161
	v_and_b32_e32 v219, 0xffff0000, v161
	v_lshlrev_b32_e32 v220, 16, v162
	v_and_b32_e32 v221, 0xffff0000, v162
	v_lshlrev_b32_e32 v222, 16, v163
	v_and_b32_e32 v223, 0xffff0000, v163
	v_pk_mul_f32 v[216:217], v[214:215], v[216:217]
	v_pk_mul_f32 v[218:219], v[214:215], v[218:219]
	v_pk_mul_f32 v[220:221], v[214:215], v[220:221]
	v_pk_mul_f32 v[222:223], v[214:215], v[222:223]
	v_pk_mul_f32 v[216:217], v[56:57], v[216:217]
	v_pk_mul_f32 v[218:219], v[58:59], v[218:219]
	v_pk_mul_f32 v[220:221], v[60:61], v[220:221]
	v_pk_mul_f32 v[222:223], v[62:63], v[222:223]
	global_store_dwordx4 v3, v[216:219], s[18:19] offset:0
	global_store_dwordx4 v3, v[220:223], s[18:19] offset:16
	v_lshlrev_b32_e32 v224, 16, v164
	v_and_b32_e32 v225, 0xffff0000, v164
	v_lshlrev_b32_e32 v226, 16, v165
	v_and_b32_e32 v227, 0xffff0000, v165
	v_lshlrev_b32_e32 v228, 16, v166
	v_and_b32_e32 v229, 0xffff0000, v166
	v_lshlrev_b32_e32 v230, 16, v167
	v_and_b32_e32 v231, 0xffff0000, v167
	v_pk_mul_f32 v[224:225], v[214:215], v[224:225]
	v_pk_mul_f32 v[226:227], v[214:215], v[226:227]
	v_pk_mul_f32 v[228:229], v[214:215], v[228:229]
	v_pk_mul_f32 v[230:231], v[214:215], v[230:231]
	v_pk_mul_f32 v[224:225], v[64:65], v[224:225]
	v_pk_mul_f32 v[226:227], v[66:67], v[226:227]
	v_pk_mul_f32 v[228:229], v[68:69], v[228:229]
	v_pk_mul_f32 v[230:231], v[70:71], v[230:231]
	global_store_dwordx4 v3, v[224:227], s[18:19] offset:2048
	global_store_dwordx4 v3, v[228:231], s[18:19] offset:2064
	s_add_i32 s26, s26, s74
	s_lshl_b32 s27, s26, 14
	s_add_u32 s12, s56, s27
	s_addc_u32 s13, s57, 0
	s_add_u32 s14, s12, 0x1000
	s_addc_u32 s15, s13, 0
	s_add_u32 s16, s14, 0x1000
	s_addc_u32 s17, s15, 0
	s_add_u32 s18, s16, 0x1000
	s_addc_u32 s19, s17, 0
	s_waitcnt vmcnt(48)
	v_ffbh_u32_e32 v208, v207
	v_min_u32_e32 v208, 32, v208
	v_lshlrev_b64 v[206:207], v208, v[206:207]
	v_min_u32_e32 v206, 1, v206
	v_or_b32_e32 v206, v207, v206
	v_cvt_f32_u32_e32 v206, v206
	v_sub_u32_e32 v208, 32, v208
	v_ldexp_f32 v208, v206, v208
	v_mul_f32_e32 v208, 0x33800000, v208
	v_fmamk_f32 v208, v208, 0x39800000, v233
	v_mul_f32_e32 v209, 0x4f800000, v208
	v_cmp_gt_f32_e32 vcc, s28, v208
	s_nop 1
	v_cndmask_b32_e32 v208, v208, v209, vcc
	v_sqrt_f32_e32 v209, v208
	s_nop 1
	v_add_u32_e32 v210, -1, v209
	v_add_u32_e32 v211, 1, v209
	v_fma_f32 v212, -v210, v209, v208
	v_fma_f32 v213, -v211, v209, v208
	v_cmp_ge_f32_e64 s[0:1], 0, v212
	s_nop 1
	v_cndmask_b32_e64 v209, v209, v210, s[0:1]
	v_cmp_lt_f32_e64 s[0:1], 0, v213
	s_nop 1
	v_cndmask_b32_e64 v209, v209, v211, s[0:1]
	v_mul_f32_e32 v210, 0x37800000, v209
	v_cndmask_b32_e32 v209, v209, v210, vcc
	v_cmp_class_f32_e32 vcc, v208, v234
	s_nop 1
	v_cndmask_b32_e32 v208, v209, v208, vcc
	v_div_scale_f32 v209, s[0:1], v208, v208, 1.0
	v_rcp_f32_e32 v211, v209
	v_div_scale_f32 v210, vcc, 1.0, v208, 1.0
	s_nop 0
	v_fma_f32 v212, -v209, v211, 1.0
	v_fmac_f32_e32 v211, v212, v211
	v_mul_f32_e32 v212, v210, v211
	v_fma_f32 v213, -v209, v212, v210
	v_fmac_f32_e32 v212, v213, v211
	v_fma_f32 v209, -v209, v212, v210
	s_nop 1
	v_div_fmas_f32 v209, v209, v211, v212
	v_div_fixup_f32 v214, v209, v208, 1.0
	v_mov_b32_e32 v215, v214
	v_lshlrev_b32_e32 v216, 16, v168
	v_and_b32_e32 v217, 0xffff0000, v168
	v_lshlrev_b32_e32 v218, 16, v169
	v_and_b32_e32 v219, 0xffff0000, v169
	v_lshlrev_b32_e32 v220, 16, v170
	v_and_b32_e32 v221, 0xffff0000, v170
	v_lshlrev_b32_e32 v222, 16, v171
	v_and_b32_e32 v223, 0xffff0000, v171
	v_pk_mul_f32 v[216:217], v[214:215], v[216:217]
	v_pk_mul_f32 v[218:219], v[214:215], v[218:219]
	v_pk_mul_f32 v[220:221], v[214:215], v[220:221]
	v_pk_mul_f32 v[222:223], v[214:215], v[222:223]
	v_pk_mul_f32 v[216:217], v[8:9], v[216:217]
	v_pk_mul_f32 v[218:219], v[10:11], v[218:219]
	v_pk_mul_f32 v[220:221], v[12:13], v[220:221]
	v_pk_mul_f32 v[222:223], v[14:15], v[222:223]
	global_store_dwordx4 v3, v[216:219], s[12:13] offset:0
	global_store_dwordx4 v3, v[220:223], s[12:13] offset:16
	v_lshlrev_b32_e32 v224, 16, v172
	v_and_b32_e32 v225, 0xffff0000, v172
	v_lshlrev_b32_e32 v226, 16, v173
	v_and_b32_e32 v227, 0xffff0000, v173
	v_lshlrev_b32_e32 v228, 16, v174
	v_and_b32_e32 v229, 0xffff0000, v174
	v_lshlrev_b32_e32 v230, 16, v175
	v_and_b32_e32 v231, 0xffff0000, v175
	v_pk_mul_f32 v[224:225], v[214:215], v[224:225]
	v_pk_mul_f32 v[226:227], v[214:215], v[226:227]
	v_pk_mul_f32 v[228:229], v[214:215], v[228:229]
	v_pk_mul_f32 v[230:231], v[214:215], v[230:231]
; __device__ __forceinline__ float bflo(unsigned w) { return __uint_as_float(w << 16); }
; __device__ __forceinline__ float bfhi(unsigned w) { return __uint_as_float(w & 0xffff0000u); }
; __device__ __forceinline__ void phase_final_norm(const bf16_t* Hb, const unsigned long long* ssq, const float* g, float* out, int gw, int ngw, int lane, float scale) {
;     for (int m = gw; m < MTOK; m += ngw) { const float rstd = scale / sqrtf((float)ssq[m] * (1.0f / 16777216.0f) * (1.0f / DM) + EPS);
;         const u32x4* xr = (const u32x4*)(Hb + (size_t)m * DM) + lane; f32x4* o = (f32x4*)(out + (size_t)m * DM); const f32x4* gr = (const f32x4*)g;
; #pragma unroll
;         for (int j = 0; j < 8; ++j) { const u32x4 r = xr[64 * j]; const int c4 = 2 * (64 * j + lane);
;             const f32x4 g0 = gr[c4], g1 = gr[c4 + 1];
;             o[c4] = (f32x4){bflo(r.x) * rstd * g0.x, bfhi(r.x) * rstd * g0.y, bflo(r.y) * rstd * g0.z, bfhi(r.y) * rstd * g0.w};
;             o[c4 + 1] = (f32x4){bflo(r.z) * rstd * g1.x, bfhi(r.z) * rstd * g1.y, bflo(r.w) * rstd * g1.z, bfhi(r.w) * rstd * g1.w}; } }
	v_pk_mul_f32 v[224:225], v[16:17], v[224:225]
	v_pk_mul_f32 v[226:227], v[18:19], v[226:227]
	v_pk_mul_f32 v[228:229], v[20:21], v[228:229]
	v_pk_mul_f32 v[230:231], v[22:23], v[230:231]
	global_store_dwordx4 v3, v[224:227], s[12:13] offset:2048
	global_store_dwordx4 v3, v[228:231], s[12:13] offset:2064
	v_lshlrev_b32_e32 v216, 16, v176
	v_and_b32_e32 v217, 0xffff0000, v176
	v_lshlrev_b32_e32 v218, 16, v177
	v_and_b32_e32 v219, 0xffff0000, v177
	v_lshlrev_b32_e32 v220, 16, v178
	v_and_b32_e32 v221, 0xffff0000, v178
	v_lshlrev_b32_e32 v222, 16, v179
	v_and_b32_e32 v223, 0xffff0000, v179
	v_pk_mul_f32 v[216:217], v[214:215], v[216:217]
	v_pk_mul_f32 v[218:219], v[214:215], v[218:219]
	v_pk_mul_f32 v[220:221], v[214:215], v[220:221]
	v_pk_mul_f32 v[222:223], v[214:215], v[222:223]
	v_pk_mul_f32 v[216:217], v[24:25], v[216:217]
	v_pk_mul_f32 v[218:219], v[26:27], v[218:219]
	v_pk_mul_f32 v[220:221], v[28:29], v[220:221]
	v_pk_mul_f32 v[222:223], v[30:31], v[222:223]
	global_store_dwordx4 v3, v[216:219], s[14:15] offset:0
	global_store_dwordx4 v3, v[220:223], s[14:15] offset:16
	v_lshlrev_b32_e32 v224, 16, v180
	v_and_b32_e32 v225, 0xffff0000, v180
	v_lshlrev_b32_e32 v226, 16, v181
	v_and_b32_e32 v227, 0xffff0000, v181
	v_lshlrev_b32_e32 v228, 16, v182
	v_and_b32_e32 v229, 0xffff0000, v182
	v_lshlrev_b32_e32 v230, 16, v183
	v_and_b32_e32 v231, 0xffff0000, v183
	v_pk_mul_f32 v[224:225], v[214:215], v[224:225]
	v_pk_mul_f32 v[226:227], v[214:215], v[226:227]
	v_pk_mul_f32 v[228:229], v[214:215], v[228:229]
	v_pk_mul_f32 v[230:231], v[214:215], v[230:231]
	v_pk_mul_f32 v[224:225], v[32:33], v[224:225]
	v_pk_mul_f32 v[226:227], v[34:35], v[226:227]
	v_pk_mul_f32 v[228:229], v[36:37], v[228:229]
	v_pk_mul_f32 v[230:231], v[38:39], v[230:231]
	global_store_dwordx4 v3, v[224:227], s[14:15] offset:2048
	global_store_dwordx4 v3, v[228:231], s[14:15] offset:2064
	v_lshlrev_b32_e32 v216, 16, v184
	v_and_b32_e32 v217, 0xffff0000, v184
	v_lshlrev_b32_e32 v218, 16, v185
	v_and_b32_e32 v219, 0xffff0000, v185
	v_lshlrev_b32_e32 v220, 16, v186
	v_and_b32_e32 v221, 0xffff0000, v186
	v_lshlrev_b32_e32 v222, 16, v187
	v_and_b32_e32 v223, 0xffff0000, v187
	v_pk_mul_f32 v[216:217], v[214:215], v[216:217]
	v_pk_mul_f32 v[218:219], v[214:215], v[218:219]
	v_pk_mul_f32 v[220:221], v[214:215], v[220:221]
	v_pk_mul_f32 v[222:223], v[214:215], v[222:223]
	v_pk_mul_f32 v[216:217], v[40:41], v[216:217]
	v_pk_mul_f32 v[218:219], v[42:43], v[218:219]
	v_pk_mul_f32 v[220:221], v[44:45], v[220:221]
	v_pk_mul_f32 v[222:223], v[46:47], v[222:223]
	global_store_dwordx4 v3, v[216:219], s[16:17] offset:0
	global_store_dwordx4 v3, v[220:223], s[16:17] offset:16
	v_lshlrev_b32_e32 v224, 16, v188
	v_and_b32_e32 v225, 0xffff0000, v188
	v_lshlrev_b32_e32 v226, 16, v189
	v_and_b32_e32 v227, 0xffff0000, v189
	v_lshlrev_b32_e32 v228, 16, v190
	v_and_b32_e32 v229, 0xffff0000, v190
	v_lshlrev_b32_e32 v230, 16, v191
	v_and_b32_e32 v231, 0xffff0000, v191
	v_pk_mul_f32 v[224:225], v[214:215], v[224:225]
	v_pk_mul_f32 v[226:227], v[214:215], v[226:227]
	v_pk_mul_f32 v[228:229], v[214:215], v[228:229]
	v_pk_mul_f32 v[230:231], v[214:215], v[230:231]
	v_pk_mul_f32 v[224:225], v[48:49], v[224:225]
	v_pk_mul_f32 v[226:227], v[50:51], v[226:227]
	v_pk_mul_f32 v[228:229], v[52:53], v[228:229]
	v_pk_mul_f32 v[230:231], v[54:55], v[230:231]
	global_store_dwordx4 v3, v[224:227], s[16:17] offset:2048
	global_store_dwordx4 v3, v[228:231], s[16:17] offset:2064
	v_lshlrev_b32_e32 v216, 16, v192
	v_and_b32_e32 v217, 0xffff0000, v192
	v_lshlrev_b32_e32 v218, 16, v193
	v_and_b32_e32 v219, 0xffff0000, v193
	v_lshlrev_b32_e32 v220, 16, v194
	v_and_b32_e32 v221, 0xffff0000, v194
	v_lshlrev_b32_e32 v222, 16, v195
	v_and_b32_e32 v223, 0xffff0000, v195
	v_pk_mul_f32 v[216:217], v[214:215], v[216:217]
	v_pk_mul_f32 v[218:219], v[214:215], v[218:219]
	v_pk_mul_f32 v[220:221], v[214:215], v[220:221]
	v_pk_mul_f32 v[222:223], v[214:215], v[222:223]
	v_pk_mul_f32 v[216:217], v[56:57], v[216:217]
	v_pk_mul_f32 v[218:219], v[58:59], v[218:219]
	v_pk_mul_f32 v[220:221], v[60:61], v[220:221]
	v_pk_mul_f32 v[222:223], v[62:63], v[222:223]
	global_store_dwordx4 v3, v[216:219], s[18:19] offset:0
	global_store_dwordx4 v3, v[220:223], s[18:19] offset:16
	v_lshlrev_b32_e32 v224, 16, v196
	v_and_b32_e32 v225, 0xffff0000, v196
	v_lshlrev_b32_e32 v226, 16, v197
	v_and_b32_e32 v227, 0xffff0000, v197
	v_lshlrev_b32_e32 v228, 16, v198
	v_and_b32_e32 v229, 0xffff0000, v198
	v_lshlrev_b32_e32 v230, 16, v199
	v_and_b32_e32 v231, 0xffff0000, v199
	v_pk_mul_f32 v[224:225], v[214:215], v[224:225]
	v_pk_mul_f32 v[226:227], v[214:215], v[226:227]
	v_pk_mul_f32 v[228:229], v[214:215], v[228:229]
	v_pk_mul_f32 v[230:231], v[214:215], v[230:231]
	v_pk_mul_f32 v[224:225], v[64:65], v[224:225]
	v_pk_mul_f32 v[226:227], v[66:67], v[226:227]
	v_pk_mul_f32 v[228:229], v[68:69], v[228:229]
	v_pk_mul_f32 v[230:231], v[70:71], v[230:231]
	global_store_dwordx4 v3, v[224:227], s[18:19] offset:2048
	global_store_dwordx4 v3, v[228:231], s[18:19] offset:2064
	s_endpgm
